# w13 weight conversion loops (layers 1-3): software prefetch of the next tile (scratch loads) while the current tile is transposed
# baseline (speedup 1.0000x reference)
.LBB0_959:
	s_or_b64 exec, exec, s[4:5]
	s_add_i32 s32, s12, s82
	s_add_i32 s33, s2, s6
	s_cmpk_lt_i32 s32, 0x580
	s_cselect_b32 s32, s32, s12
	s_cselect_b32 s33, s33, s2
	s_mul_hi_i32 s34, s32, 0x2e8ba2e9
	s_lshr_b32 s35, s34, 31
	s_ashr_i32 s53, s34, 4
	s_add_i32 s54, s53, s35
	s_mul_i32 s55, s54, 0xffffea00
	s_add_i32 s56, s55, s33
	v_add_u32_e32 v30, s56, v12
	v_ashrrev_i32_e32 v56, 1, v30
	v_and_b32_e32 v58, -16, v56
	v_add_u32_e32 v60, v58, v13
	v_max_i32_e32 v60, 0, v60
	s_lshl_b32 s57, s54, 6
	v_or_b32_e32 v62, v60, v159
	v_max_i32_e32 v62, 0, v62
	v_mov_b32_e32 v63, v9
	v_lshl_add_u64 v[64:65], v[62:63], 2, s[0:1]
	v_or_b32_e32 v66, s57, v128
	v_add_u32_e32 v68, s57, v16
	v_mad_i64_i32 v[70:71], s[60:61], v66, s7, v[64:65]
	v_mad_i64_i32 v[72:73], s[62:63], v68, s7, v[64:65]
	global_load_dwordx4 v[74:77], v[70:71], off
	global_load_dwordx4 v[74:77], v[72:73], off
	s_waitcnt vmcnt(3)
	ds_write2_b32 v17, v4, v5 offset1:1
	ds_write2_b32 v17, v6, v7 offset0:2 offset1:3
	s_waitcnt vmcnt(2)
	ds_write2_b32 v18, v0, v1 offset1:1
	ds_write2_b32 v19, v2, v3 offset1:1
	s_waitcnt lgkmcnt(0)
	s_barrier
	ds_read2_b32 v[0:1], v15 offset1:65
	ds_read2_b32 v[2:3], v15 offset0:130 offset1:195
	ds_read2_b32 v[4:5], v20 offset0:4 offset1:69
	ds_read2_b32 v[6:7], v20 offset0:134 offset1:199
	v_readlane_b32 s4, v255, 27
	s_waitcnt lgkmcnt(3)
	v_cvt_pk_bf16_f32 v0, v0, v1
	s_waitcnt lgkmcnt(2)
	v_cvt_pk_bf16_f32 v1, v2, v3
	s_waitcnt lgkmcnt(1)
	v_cvt_pk_bf16_f32 v2, v4, v5
	v_add_u32_e32 v4, s9, v14
	v_ashrrev_i32_e32 v5, 31, v4
	v_lshlrev_b64 v[4:5], 11, v[4:5]
	v_readlane_b32 s5, v255, 28
	s_ashr_i32 s9, s8, 31
	s_add_i32 s12, s12, s82
	v_lshl_add_u64 v[4:5], s[4:5], 0, v[4:5]
	v_lshl_add_u64 v[4:5], s[8:9], 1, v[4:5]
	s_add_i32 s2, s2, s6
	s_waitcnt lgkmcnt(0)
	v_cvt_pk_bf16_f32 v3, v6, v7
	v_lshl_add_u64 v[4:5], v[4:5], 0, v[10:11]
	s_cmpk_lt_i32 s12, 0x580
	global_store_dwordx4 v[4:5], v[0:3], off
	s_cbranch_scc0 .LBB0_962

.LBB0_1003:
	s_or_b64 exec, exec, s[4:5]
	s_add_i32 s32, s14, s82
	s_add_i32 s33, s2, s6
	s_cmpk_lt_i32 s32, 0x580
	s_cselect_b32 s32, s32, s14
	s_cselect_b32 s33, s33, s2
	s_mul_hi_i32 s34, s32, 0x2e8ba2e9
	s_lshr_b32 s35, s34, 31
	s_ashr_i32 s53, s34, 4
	s_add_i32 s54, s53, s35
	s_mul_i32 s55, s54, 0xffffea00
	s_add_i32 s56, s55, s33
	v_add_u32_e32 v24, s56, v131
	v_ashrrev_i32_e32 v26, 1, v24
	v_and_b32_e32 v28, -16, v26
	v_add_u32_e32 v30, v28, v12
	v_max_i32_e32 v30, 0, v30
	s_lshl_b32 s57, s54, 6
	v_or_b32_e32 v32, v30, v159
	v_max_i32_e32 v32, 0, v32
	v_mov_b32_e32 v33, v9
	v_lshl_add_u64 v[34:35], v[32:33], 2, s[0:1]
	v_or_b32_e32 v36, s57, v128
	v_add_u32_e32 v38, s57, v14
	v_mad_i64_i32 v[40:41], s[62:63], v36, s7, v[34:35]
	v_mad_i64_i32 v[42:43], s[64:65], v38, s7, v[34:35]
	global_load_dwordx4 v[44:47], v[40:41], off
	global_load_dwordx4 v[44:47], v[42:43], off
	s_waitcnt vmcnt(3)
	ds_write2_b32 v15, v4, v5 offset1:1
	ds_write2_b32 v15, v6, v7 offset0:2 offset1:3
	s_waitcnt vmcnt(2)
	ds_write2_b32 v16, v0, v1 offset1:1
	ds_write2_b32 v17, v2, v3 offset1:1
	s_waitcnt lgkmcnt(0)
	s_barrier
	ds_read2_b32 v[0:1], v13 offset1:65
	ds_read2_b32 v[2:3], v13 offset0:130 offset1:195
	ds_read2_b32 v[4:5], v18 offset0:4 offset1:69
	ds_read2_b32 v[6:7], v18 offset0:134 offset1:199
	v_readlane_b32 s4, v255, 33
	s_waitcnt lgkmcnt(3)
	v_cvt_pk_bf16_f32 v0, v0, v1
	s_waitcnt lgkmcnt(2)
	v_cvt_pk_bf16_f32 v1, v2, v3
	s_waitcnt lgkmcnt(1)
	v_cvt_pk_bf16_f32 v2, v4, v5
	v_add_u32_e32 v4, s9, v154
	v_ashrrev_i32_e32 v5, 31, v4
	v_lshlrev_b64 v[4:5], 11, v[4:5]
	v_readlane_b32 s5, v255, 34
	s_ashr_i32 s9, s8, 31
	s_add_i32 s14, s14, s82
	v_lshl_add_u64 v[4:5], s[4:5], 0, v[4:5]
	v_lshl_add_u64 v[4:5], s[8:9], 1, v[4:5]
	s_add_i32 s2, s2, s6
	s_waitcnt lgkmcnt(0)
	v_cvt_pk_bf16_f32 v3, v6, v7
	v_lshl_add_u64 v[4:5], v[4:5], 0, v[10:11]
	s_cmpk_lt_i32 s14, 0x580
	global_store_dwordx4 v[4:5], v[0:3], off
	s_cbranch_scc0 .LBB0_1006

.LBB0_1027:
	s_or_b64 exec, exec, s[4:5]
	s_add_i32 s32, s10, s82
	s_add_i32 s33, s2, s6
	s_cmpk_lt_i32 s32, 0x580
	s_cselect_b32 s32, s32, s10
	s_cselect_b32 s33, s33, s2
	s_mul_hi_i32 s34, s32, 0x2e8ba2e9
	s_lshr_b32 s35, s34, 31
	s_ashr_i32 s53, s34, 4
	s_add_i32 s54, s53, s35
	s_mul_i32 s55, s54, 0xffffea00
	s_add_i32 s62, s55, s33
	v_add_u32_e32 v24, s62, v131
	v_ashrrev_i32_e32 v26, 1, v24
	v_and_b32_e32 v28, -16, v26
	v_add_u32_e32 v30, v28, v12
	v_max_i32_e32 v30, 0, v30
	s_lshl_b32 s63, s54, 6
	v_or_b32_e32 v32, v30, v159
	v_max_i32_e32 v32, 0, v32
	v_mov_b32_e32 v33, v9
	v_lshl_add_u64 v[34:35], v[32:33], 2, s[0:1]
	v_or_b32_e32 v36, s63, v128
	v_add_u32_e32 v38, s63, v14
	v_mad_i64_i32 v[40:41], s[68:69], v36, s7, v[34:35]
	v_mad_i64_i32 v[42:43], s[70:71], v38, s7, v[34:35]
	global_load_dwordx4 v[44:47], v[40:41], off
	global_load_dwordx4 v[44:47], v[42:43], off
	s_waitcnt vmcnt(3)
	ds_write2_b32 v15, v4, v5 offset1:1
	ds_write2_b32 v15, v6, v7 offset0:2 offset1:3
	s_waitcnt vmcnt(2)
	ds_write2_b32 v16, v0, v1 offset1:1
	ds_write2_b32 v17, v2, v3 offset1:1
	s_waitcnt lgkmcnt(0)
	s_barrier
	ds_read2_b32 v[0:1], v13 offset1:65
	ds_read2_b32 v[2:3], v13 offset0:130 offset1:195
	ds_read2_b32 v[4:5], v18 offset0:4 offset1:69
	ds_read2_b32 v[6:7], v18 offset0:134 offset1:199
	v_readlane_b32 s4, v254, 41
	s_waitcnt lgkmcnt(3)
	v_cvt_pk_bf16_f32 v0, v0, v1
	s_waitcnt lgkmcnt(2)
	v_cvt_pk_bf16_f32 v1, v2, v3
	s_waitcnt lgkmcnt(1)
	v_cvt_pk_bf16_f32 v2, v4, v5
	v_add_u32_e32 v4, s9, v154
	v_ashrrev_i32_e32 v5, 31, v4
	v_lshlrev_b64 v[4:5], 11, v[4:5]
	v_readlane_b32 s5, v254, 42
	s_ashr_i32 s9, s8, 31
	s_add_i32 s10, s10, s82
	v_lshl_add_u64 v[4:5], s[4:5], 0, v[4:5]
	v_lshl_add_u64 v[4:5], s[8:9], 1, v[4:5]
	s_add_i32 s2, s2, s6
	s_waitcnt lgkmcnt(0)
	v_cvt_pk_bf16_f32 v3, v6, v7
	v_lshl_add_u64 v[4:5], v[4:5], 0, v[10:11]
	s_cmpk_lt_i32 s10, 0x580
	global_store_dwordx4 v[4:5], v[0:3], off
	s_cbranch_scc0 .LBB0_1030
